# v16 + tile-start barrier in the 128x256 K-loops (closes a theoretical LDS WAR between consecutive tiles)
# baseline (speedup 1.0000x reference)
.LBB0_96:
	s_andn2_b64 vcc, exec, s[2:3]
	s_cbranch_vccnz .LBB0_90
	v_readlane_b32 s2, v253, 4
	v_readlane_b32 s3, v253, 5
	s_lshl_b32 s13, s54, 18
	s_add_u32 s2, s2, s13
	s_addc_u32 s3, s3, 0
	s_lshl_b32 s13, s56, 19
	s_add_u32 s4, s50, 0x4490000
	s_addc_u32 s5, s51, 0
	s_add_u32 s4, s4, s13
	s_addc_u32 s5, s5, 0
	v_and_b32_e32 v152, 63, v216
	v_lshrrev_b32_e32 v153, 6, v216
	v_lshrrev_b32_e32 v154, 2, v152
	v_and_b32_e32 v155, 3, v152
	v_readfirstlane_b32 s11, v153
	v_lshrrev_b32_e32 v156, 3, v154
	v_mul_u32_u24_e32 v156, 3, v156
	v_xor_b32_e32 v156, v155, v156
	v_lshlrev_b32_e32 v156, 4, v156
	v_lshl_add_u32 v157, v153, 5, v154
	v_lshl_add_u32 v203, v157, 11, v156
	v_add_u32_e32 v204, 0x8000, v203
	v_lshl_add_u32 v157, v153, 6, v154
	v_lshl_add_u32 v205, v157, 11, v156
	v_add_u32_e32 v206, 0x8000, v205
	v_add_u32_e32 v207, 0x10000, v205
	v_add_u32_e32 v208, 0x18000, v205
	v_and_b32_e32 v158, 15, v152
	v_lshrrev_b32_e32 v159, 4, v152
	v_lshrrev_b32_e32 v160, 3, v158
	v_mul_u32_u24_e32 v160, 3, v160
	v_xor_b32_e32 v160, v159, v160
	v_lshlrev_b32_e32 v160, 4, v160
	v_lshl_add_u32 v160, v158, 6, v160
	v_lshrrev_b32_e32 v161, 1, v153
	v_and_b32_e32 v162, 1, v153
	v_lshl_add_u32 v209, v161, 12, v160
	v_lshl_add_u32 v210, v162, 13, v160
	s_lshl_b32 s12, s11, 12
	s_lshl_b32 s11, s11, 11
	s_barrier
	s_add_u32 m0, s11, 0x0
	s_nop 0
	global_load_lds_dwordx4 v203, s[2:3]
	s_add_u32 m0, s11, 0x400
	s_nop 0
	global_load_lds_dwordx4 v204, s[2:3]
	s_add_u32 m0, s12, 0x2000
	s_nop 0
	global_load_lds_dwordx4 v205, s[4:5]
	s_add_u32 m0, s12, 0x2400
	s_nop 0
	global_load_lds_dwordx4 v206, s[4:5]
	s_add_u32 m0, s12, 0x2800
	s_nop 0
	global_load_lds_dwordx4 v207, s[4:5]
	s_add_u32 m0, s12, 0x2c00
	s_nop 0
	global_load_lds_dwordx4 v208, s[4:5]
	s_add_u32 s2, s2, 0x40
	s_addc_u32 s3, s3, 0
	s_add_u32 s4, s4, 0x40
	s_addc_u32 s5, s5, 0
	s_add_u32 m0, s11, 0x6000
	s_nop 0
	global_load_lds_dwordx4 v203, s[2:3]
	s_add_u32 m0, s11, 0x6400
	s_nop 0
	global_load_lds_dwordx4 v204, s[2:3]
	s_add_u32 m0, s12, 0x8000
	s_nop 0
	global_load_lds_dwordx4 v205, s[4:5]
	s_add_u32 m0, s12, 0x8400
	s_nop 0
	global_load_lds_dwordx4 v206, s[4:5]
	s_add_u32 m0, s12, 0x8800
	s_nop 0
	global_load_lds_dwordx4 v207, s[4:5]
	s_add_u32 m0, s12, 0x8c00
	s_nop 0
	global_load_lds_dwordx4 v208, s[4:5]
	s_add_u32 s2, s2, 0x40
	s_addc_u32 s3, s3, 0
	s_add_u32 s4, s4, 0x40
	s_addc_u32 s5, s5, 0
	v_mov_b32_e32 v172, 0
	v_mov_b32_e32 v173, 0
	v_mov_b32_e32 v174, 0
	v_mov_b32_e32 v175, 0
	v_mov_b32_e32 v168, 0
	v_mov_b32_e32 v169, 0
	v_mov_b32_e32 v170, 0
	v_mov_b32_e32 v171, 0
	v_mov_b32_e32 v116, 0
	v_mov_b32_e32 v117, 0
	v_mov_b32_e32 v118, 0
	v_mov_b32_e32 v119, 0
	v_mov_b32_e32 v112, 0
	v_mov_b32_e32 v113, 0
	v_mov_b32_e32 v114, 0
	v_mov_b32_e32 v115, 0
	v_mov_b32_e32 v108, 0
	v_mov_b32_e32 v109, 0
	v_mov_b32_e32 v110, 0
	v_mov_b32_e32 v111, 0
	v_mov_b32_e32 v104, 0
	v_mov_b32_e32 v105, 0
	v_mov_b32_e32 v106, 0
	v_mov_b32_e32 v107, 0
	v_mov_b32_e32 v100, 0
	v_mov_b32_e32 v101, 0
	v_mov_b32_e32 v102, 0
	v_mov_b32_e32 v103, 0
	v_mov_b32_e32 v96, 0
	v_mov_b32_e32 v97, 0
	v_mov_b32_e32 v98, 0
	v_mov_b32_e32 v99, 0
	v_mov_b32_e32 v92, 0
	v_mov_b32_e32 v93, 0
	v_mov_b32_e32 v94, 0
	v_mov_b32_e32 v95, 0
	v_mov_b32_e32 v88, 0
	v_mov_b32_e32 v89, 0
	v_mov_b32_e32 v90, 0
	v_mov_b32_e32 v91, 0
	v_mov_b32_e32 v84, 0
	v_mov_b32_e32 v85, 0
	v_mov_b32_e32 v86, 0
	v_mov_b32_e32 v87, 0
	v_mov_b32_e32 v80, 0
	v_mov_b32_e32 v81, 0
	v_mov_b32_e32 v82, 0
	v_mov_b32_e32 v83, 0
	v_mov_b32_e32 v76, 0
	v_mov_b32_e32 v77, 0
	v_mov_b32_e32 v78, 0
	v_mov_b32_e32 v79, 0
	v_mov_b32_e32 v72, 0
	v_mov_b32_e32 v73, 0
	v_mov_b32_e32 v74, 0
	v_mov_b32_e32 v75, 0
	v_mov_b32_e32 v68, 0
	v_mov_b32_e32 v69, 0
	v_mov_b32_e32 v70, 0
	v_mov_b32_e32 v71, 0
	v_mov_b32_e32 v64, 0
	v_mov_b32_e32 v65, 0
	v_mov_b32_e32 v66, 0
	v_mov_b32_e32 v67, 0
	v_mov_b32_e32 v60, 0
	v_mov_b32_e32 v61, 0
	v_mov_b32_e32 v62, 0
	v_mov_b32_e32 v63, 0
	v_mov_b32_e32 v56, 0
	v_mov_b32_e32 v57, 0
	v_mov_b32_e32 v58, 0
	v_mov_b32_e32 v59, 0
	v_mov_b32_e32 v52, 0
	v_mov_b32_e32 v53, 0
	v_mov_b32_e32 v54, 0
	v_mov_b32_e32 v55, 0
	v_mov_b32_e32 v48, 0
	v_mov_b32_e32 v49, 0
	v_mov_b32_e32 v50, 0
	v_mov_b32_e32 v51, 0
	v_mov_b32_e32 v44, 0
	v_mov_b32_e32 v45, 0
	v_mov_b32_e32 v46, 0
	v_mov_b32_e32 v47, 0
	v_mov_b32_e32 v40, 0
	v_mov_b32_e32 v41, 0
	v_mov_b32_e32 v42, 0
	v_mov_b32_e32 v43, 0
	v_mov_b32_e32 v36, 0
	v_mov_b32_e32 v37, 0
	v_mov_b32_e32 v38, 0
	v_mov_b32_e32 v39, 0
	v_mov_b32_e32 v32, 0
	v_mov_b32_e32 v33, 0
	v_mov_b32_e32 v34, 0
	v_mov_b32_e32 v35, 0
	v_mov_b32_e32 v28, 0
	v_mov_b32_e32 v29, 0
	v_mov_b32_e32 v30, 0
	v_mov_b32_e32 v31, 0
	v_mov_b32_e32 v24, 0
	v_mov_b32_e32 v25, 0
	v_mov_b32_e32 v26, 0
	v_mov_b32_e32 v27, 0
	v_mov_b32_e32 v20, 0
	v_mov_b32_e32 v21, 0
	v_mov_b32_e32 v22, 0
	v_mov_b32_e32 v23, 0
	v_mov_b32_e32 v16, 0
	v_mov_b32_e32 v17, 0
	v_mov_b32_e32 v18, 0
	v_mov_b32_e32 v19, 0
	v_mov_b32_e32 v12, 0
	v_mov_b32_e32 v13, 0
	v_mov_b32_e32 v14, 0
	v_mov_b32_e32 v15, 0
	v_mov_b32_e32 v8, 0
	v_mov_b32_e32 v9, 0
	v_mov_b32_e32 v10, 0
	v_mov_b32_e32 v11, 0
	v_mov_b32_e32 v4, 0
	v_mov_b32_e32 v5, 0
	v_mov_b32_e32 v6, 0
	v_mov_b32_e32 v7, 0
	v_mov_b32_e32 v0, 0
	v_mov_b32_e32 v1, 0
	v_mov_b32_e32 v2, 0
	v_mov_b32_e32 v3, 0
	s_waitcnt vmcnt(6)
	s_barrier
	ds_read_b128 v[120:123], v209 offset:0
	ds_read_b128 v[124:127], v209 offset:1024
	ds_read_b128 v[128:131], v209 offset:2048
	ds_read_b128 v[132:135], v209 offset:3072
	ds_read_b128 v[152:155], v210 offset:8192
	ds_read_b128 v[156:159], v210 offset:9216
	ds_read_b128 v[160:163], v210 offset:10240
	ds_read_b128 v[164:167], v210 offset:11264
	ds_read_b128 v[176:179], v210 offset:12288
	ds_read_b128 v[180:183], v210 offset:13312
	s_add_u32 m0, s11, 0xc000
	s_nop 0
	global_load_lds_dwordx4 v203, s[2:3]
	s_add_u32 m0, s11, 0xc400
	s_nop 0
	global_load_lds_dwordx4 v204, s[2:3]
	s_add_u32 m0, s12, 0xe000
	s_nop 0
	global_load_lds_dwordx4 v205, s[4:5]
	s_add_u32 m0, s12, 0xe400
	s_nop 0
	global_load_lds_dwordx4 v206, s[4:5]
	s_add_u32 m0, s12, 0xe800
	s_nop 0
	global_load_lds_dwordx4 v207, s[4:5]
	s_add_u32 m0, s12, 0xec00
	s_nop 0
	global_load_lds_dwordx4 v208, s[4:5]
	s_add_u32 s2, s2, 0x40
	s_addc_u32 s3, s3, 0
	s_add_u32 s4, s4, 0x40
	s_addc_u32 s5, s5, 0
	ds_read_b128 v[184:187], v210 offset:14336
	ds_read_b128 v[188:191], v210 offset:15360
	s_waitcnt lgkmcnt(7)
	v_mfma_f32_16x16x32_bf16 v[172:175], v[152:155], v[120:123], v[172:175]
	v_mfma_f32_16x16x32_bf16 v[92:95], v[152:155], v[124:127], v[92:95]
	v_mfma_f32_16x16x32_bf16 v[60:63], v[152:155], v[128:131], v[60:63]
	v_mfma_f32_16x16x32_bf16 v[28:31], v[152:155], v[132:135], v[28:31]
	s_waitcnt lgkmcnt(6)
	v_mfma_f32_16x16x32_bf16 v[168:171], v[156:159], v[120:123], v[168:171]
	v_mfma_f32_16x16x32_bf16 v[88:91], v[156:159], v[124:127], v[88:91]
	v_mfma_f32_16x16x32_bf16 v[56:59], v[156:159], v[128:131], v[56:59]
	v_mfma_f32_16x16x32_bf16 v[24:27], v[156:159], v[132:135], v[24:27]
	s_waitcnt lgkmcnt(5)
	v_mfma_f32_16x16x32_bf16 v[116:119], v[160:163], v[120:123], v[116:119]
	v_mfma_f32_16x16x32_bf16 v[84:87], v[160:163], v[124:127], v[84:87]
	v_mfma_f32_16x16x32_bf16 v[52:55], v[160:163], v[128:131], v[52:55]
	v_mfma_f32_16x16x32_bf16 v[20:23], v[160:163], v[132:135], v[20:23]
	s_waitcnt lgkmcnt(4)
	v_mfma_f32_16x16x32_bf16 v[112:115], v[164:167], v[120:123], v[112:115]
	v_mfma_f32_16x16x32_bf16 v[80:83], v[164:167], v[124:127], v[80:83]
	v_mfma_f32_16x16x32_bf16 v[48:51], v[164:167], v[128:131], v[48:51]
	v_mfma_f32_16x16x32_bf16 v[16:19], v[164:167], v[132:135], v[16:19]
	s_waitcnt lgkmcnt(3)
	v_mfma_f32_16x16x32_bf16 v[108:111], v[176:179], v[120:123], v[108:111]
	v_mfma_f32_16x16x32_bf16 v[76:79], v[176:179], v[124:127], v[76:79]
	v_mfma_f32_16x16x32_bf16 v[44:47], v[176:179], v[128:131], v[44:47]
	v_mfma_f32_16x16x32_bf16 v[12:15], v[176:179], v[132:135], v[12:15]
	s_waitcnt lgkmcnt(2)
	v_mfma_f32_16x16x32_bf16 v[104:107], v[180:183], v[120:123], v[104:107]
	v_mfma_f32_16x16x32_bf16 v[72:75], v[180:183], v[124:127], v[72:75]
	v_mfma_f32_16x16x32_bf16 v[40:43], v[180:183], v[128:131], v[40:43]
	v_mfma_f32_16x16x32_bf16 v[8:11], v[180:183], v[132:135], v[8:11]
	s_waitcnt lgkmcnt(0)
	s_mov_b32 s13, 5

.LBB0_509:
	s_andn2_b64 vcc, exec, s[2:3]
	s_cbranch_vccnz .LBB0_503
	v_readlane_b32 s11, v255, 8
	v_readlane_b32 s12, v255, 6
	v_readlane_b32 s2, v253, 4
	v_readlane_b32 s3, v253, 5
	s_lshl_b32 s13, s11, 18
	s_add_u32 s2, s2, s13
	s_addc_u32 s3, s3, 0
	s_lshl_b32 s13, s12, 19
	s_add_u32 s4, s50, 0x5510000
	s_addc_u32 s5, s51, 0
	s_add_u32 s4, s4, s13
	s_addc_u32 s5, s5, 0
	v_and_b32_e32 v92, 63, v216
	v_lshrrev_b32_e32 v93, 6, v216
	v_lshrrev_b32_e32 v94, 2, v92
	v_and_b32_e32 v95, 3, v92
	v_readfirstlane_b32 s11, v93
	v_lshrrev_b32_e32 v100, 3, v94
	v_mul_u32_u24_e32 v100, 3, v100
	v_xor_b32_e32 v100, v95, v100
	v_lshlrev_b32_e32 v100, 4, v100
	v_lshl_add_u32 v101, v93, 5, v94
	v_lshl_add_u32 v203, v101, 11, v100
	v_add_u32_e32 v204, 0x8000, v203
	v_lshl_add_u32 v101, v93, 6, v94
	v_lshl_add_u32 v205, v101, 11, v100
	v_add_u32_e32 v206, 0x8000, v205
	v_add_u32_e32 v207, 0x10000, v205
	v_add_u32_e32 v208, 0x18000, v205
	v_and_b32_e32 v102, 15, v92
	v_lshrrev_b32_e32 v103, 4, v92
	v_lshrrev_b32_e32 v108, 3, v102
	v_mul_u32_u24_e32 v108, 3, v108
	v_xor_b32_e32 v108, v103, v108
	v_lshlrev_b32_e32 v108, 4, v108
	v_lshl_add_u32 v108, v102, 6, v108
	v_lshrrev_b32_e32 v109, 1, v93
	v_and_b32_e32 v110, 1, v93
	v_lshl_add_u32 v209, v109, 12, v108
	v_lshl_add_u32 v210, v110, 13, v108
	s_lshl_b32 s12, s11, 12
	s_lshl_b32 s11, s11, 11
	s_barrier
	s_add_u32 m0, s11, 0x0
	s_nop 0
	global_load_lds_dwordx4 v203, s[2:3]
	s_add_u32 m0, s11, 0x400
	s_nop 0
	global_load_lds_dwordx4 v204, s[2:3]
	s_add_u32 m0, s12, 0x2000
	s_nop 0
	global_load_lds_dwordx4 v205, s[4:5]
	s_add_u32 m0, s12, 0x2400
	s_nop 0
	global_load_lds_dwordx4 v206, s[4:5]
	s_add_u32 m0, s12, 0x2800
	s_nop 0
	global_load_lds_dwordx4 v207, s[4:5]
	s_add_u32 m0, s12, 0x2c00
	s_nop 0
	global_load_lds_dwordx4 v208, s[4:5]
	s_add_u32 s2, s2, 0x40
	s_addc_u32 s3, s3, 0
	s_add_u32 s4, s4, 0x40
	s_addc_u32 s5, s5, 0
	s_add_u32 m0, s11, 0x6000
	s_nop 0
	global_load_lds_dwordx4 v203, s[2:3]
	s_add_u32 m0, s11, 0x6400
	s_nop 0
	global_load_lds_dwordx4 v204, s[2:3]
	s_add_u32 m0, s12, 0x8000
	s_nop 0
	global_load_lds_dwordx4 v205, s[4:5]
	s_add_u32 m0, s12, 0x8400
	s_nop 0
	global_load_lds_dwordx4 v206, s[4:5]
	s_add_u32 m0, s12, 0x8800
	s_nop 0
	global_load_lds_dwordx4 v207, s[4:5]
	s_add_u32 m0, s12, 0x8c00
	s_nop 0
	global_load_lds_dwordx4 v208, s[4:5]
	s_add_u32 s2, s2, 0x40
	s_addc_u32 s3, s3, 0
	s_add_u32 s4, s4, 0x40
	s_addc_u32 s5, s5, 0
	v_mov_b32_e32 v156, 0
	v_mov_b32_e32 v157, 0
	v_mov_b32_e32 v158, 0
	v_mov_b32_e32 v159, 0
	v_mov_b32_e32 v152, 0
	v_mov_b32_e32 v153, 0
	v_mov_b32_e32 v154, 0
	v_mov_b32_e32 v155, 0
	v_mov_b32_e32 v148, 0
	v_mov_b32_e32 v149, 0
	v_mov_b32_e32 v150, 0
	v_mov_b32_e32 v151, 0
	v_mov_b32_e32 v144, 0
	v_mov_b32_e32 v145, 0
	v_mov_b32_e32 v146, 0
	v_mov_b32_e32 v147, 0
	v_mov_b32_e32 v172, 0
	v_mov_b32_e32 v173, 0
	v_mov_b32_e32 v174, 0
	v_mov_b32_e32 v175, 0
	v_mov_b32_e32 v168, 0
	v_mov_b32_e32 v169, 0
	v_mov_b32_e32 v170, 0
	v_mov_b32_e32 v171, 0
	v_mov_b32_e32 v164, 0
	v_mov_b32_e32 v165, 0
	v_mov_b32_e32 v166, 0
	v_mov_b32_e32 v167, 0
	v_mov_b32_e32 v160, 0
	v_mov_b32_e32 v161, 0
	v_mov_b32_e32 v162, 0
	v_mov_b32_e32 v163, 0
	v_mov_b32_e32 v124, 0
	v_mov_b32_e32 v125, 0
	v_mov_b32_e32 v126, 0
	v_mov_b32_e32 v127, 0
	v_mov_b32_e32 v120, 0
	v_mov_b32_e32 v121, 0
	v_mov_b32_e32 v122, 0
	v_mov_b32_e32 v123, 0
	v_mov_b32_e32 v112, 0
	v_mov_b32_e32 v113, 0
	v_mov_b32_e32 v114, 0
	v_mov_b32_e32 v115, 0
	v_mov_b32_e32 v104, 0
	v_mov_b32_e32 v105, 0
	v_mov_b32_e32 v106, 0
	v_mov_b32_e32 v107, 0
	v_mov_b32_e32 v140, 0
	v_mov_b32_e32 v141, 0
	v_mov_b32_e32 v142, 0
	v_mov_b32_e32 v143, 0
	v_mov_b32_e32 v136, 0
	v_mov_b32_e32 v137, 0
	v_mov_b32_e32 v138, 0
	v_mov_b32_e32 v139, 0
	v_mov_b32_e32 v132, 0
	v_mov_b32_e32 v133, 0
	v_mov_b32_e32 v134, 0
	v_mov_b32_e32 v135, 0
	v_mov_b32_e32 v128, 0
	v_mov_b32_e32 v129, 0
	v_mov_b32_e32 v130, 0
	v_mov_b32_e32 v131, 0
	v_mov_b32_e32 v52, 0
	v_mov_b32_e32 v53, 0
	v_mov_b32_e32 v54, 0
	v_mov_b32_e32 v55, 0
	v_mov_b32_e32 v40, 0
	v_mov_b32_e32 v41, 0
	v_mov_b32_e32 v42, 0
	v_mov_b32_e32 v43, 0
	v_mov_b32_e32 v36, 0
	v_mov_b32_e32 v37, 0
	v_mov_b32_e32 v38, 0
	v_mov_b32_e32 v39, 0
	v_mov_b32_e32 v32, 0
	v_mov_b32_e32 v33, 0
	v_mov_b32_e32 v34, 0
	v_mov_b32_e32 v35, 0
	v_mov_b32_e32 v96, 0
	v_mov_b32_e32 v97, 0
	v_mov_b32_e32 v98, 0
	v_mov_b32_e32 v99, 0
	v_mov_b32_e32 v88, 0
	v_mov_b32_e32 v89, 0
	v_mov_b32_e32 v90, 0
	v_mov_b32_e32 v91, 0
	v_mov_b32_e32 v76, 0
	v_mov_b32_e32 v77, 0
	v_mov_b32_e32 v78, 0
	v_mov_b32_e32 v79, 0
	v_mov_b32_e32 v68, 0
	v_mov_b32_e32 v69, 0
	v_mov_b32_e32 v70, 0
	v_mov_b32_e32 v71, 0
	v_mov_b32_e32 v12, 0
	v_mov_b32_e32 v13, 0
	v_mov_b32_e32 v14, 0
	v_mov_b32_e32 v15, 0
	v_mov_b32_e32 v8, 0
	v_mov_b32_e32 v9, 0
	v_mov_b32_e32 v10, 0
	v_mov_b32_e32 v11, 0
	v_mov_b32_e32 v4, 0
	v_mov_b32_e32 v5, 0
	v_mov_b32_e32 v6, 0
	v_mov_b32_e32 v7, 0
	v_mov_b32_e32 v0, 0
	v_mov_b32_e32 v1, 0
	v_mov_b32_e32 v2, 0
	v_mov_b32_e32 v3, 0
	v_mov_b32_e32 v28, 0
	v_mov_b32_e32 v29, 0
	v_mov_b32_e32 v30, 0
	v_mov_b32_e32 v31, 0
	v_mov_b32_e32 v24, 0
	v_mov_b32_e32 v25, 0
	v_mov_b32_e32 v26, 0
	v_mov_b32_e32 v27, 0
	v_mov_b32_e32 v20, 0
	v_mov_b32_e32 v21, 0
	v_mov_b32_e32 v22, 0
	v_mov_b32_e32 v23, 0
	v_mov_b32_e32 v16, 0
	v_mov_b32_e32 v17, 0
	v_mov_b32_e32 v18, 0
	v_mov_b32_e32 v19, 0
	s_waitcnt vmcnt(6)
	s_barrier
	ds_read_b128 v[44:47], v209 offset:0
	ds_read_b128 v[48:51], v209 offset:1024
	ds_read_b128 v[56:59], v209 offset:2048
	ds_read_b128 v[60:63], v209 offset:3072
	ds_read_b128 v[92:95], v210 offset:8192
	ds_read_b128 v[100:103], v210 offset:9216
	ds_read_b128 v[108:111], v210 offset:10240
	ds_read_b128 v[116:119], v210 offset:11264
	ds_read_b128 v[176:179], v210 offset:12288
	ds_read_b128 v[180:183], v210 offset:13312
	s_add_u32 m0, s11, 0xc000
	s_nop 0
	global_load_lds_dwordx4 v203, s[2:3]
	s_add_u32 m0, s11, 0xc400
	s_nop 0
	global_load_lds_dwordx4 v204, s[2:3]
	s_add_u32 m0, s12, 0xe000
	s_nop 0
	global_load_lds_dwordx4 v205, s[4:5]
	s_add_u32 m0, s12, 0xe400
	s_nop 0
	global_load_lds_dwordx4 v206, s[4:5]
	s_add_u32 m0, s12, 0xe800
	s_nop 0
	global_load_lds_dwordx4 v207, s[4:5]
	s_add_u32 m0, s12, 0xec00
	s_nop 0
	global_load_lds_dwordx4 v208, s[4:5]
	s_add_u32 s2, s2, 0x40
	s_addc_u32 s3, s3, 0
	s_add_u32 s4, s4, 0x40
	s_addc_u32 s5, s5, 0
	ds_read_b128 v[184:187], v210 offset:14336
	ds_read_b128 v[188:191], v210 offset:15360
	s_waitcnt lgkmcnt(7)
	v_mfma_f32_16x16x32_bf16 v[156:159], v[92:95], v[44:47], v[156:159]
	v_mfma_f32_16x16x32_bf16 v[124:127], v[92:95], v[48:51], v[124:127]
	v_mfma_f32_16x16x32_bf16 v[52:55], v[92:95], v[56:59], v[52:55]
	v_mfma_f32_16x16x32_bf16 v[12:15], v[92:95], v[60:63], v[12:15]
	s_waitcnt lgkmcnt(6)
	v_mfma_f32_16x16x32_bf16 v[152:155], v[100:103], v[44:47], v[152:155]
	v_mfma_f32_16x16x32_bf16 v[120:123], v[100:103], v[48:51], v[120:123]
	v_mfma_f32_16x16x32_bf16 v[40:43], v[100:103], v[56:59], v[40:43]
	v_mfma_f32_16x16x32_bf16 v[8:11], v[100:103], v[60:63], v[8:11]
	s_waitcnt lgkmcnt(5)
	v_mfma_f32_16x16x32_bf16 v[148:151], v[108:111], v[44:47], v[148:151]
	v_mfma_f32_16x16x32_bf16 v[112:115], v[108:111], v[48:51], v[112:115]
	v_mfma_f32_16x16x32_bf16 v[36:39], v[108:111], v[56:59], v[36:39]
	v_mfma_f32_16x16x32_bf16 v[4:7], v[108:111], v[60:63], v[4:7]
	s_waitcnt lgkmcnt(4)
	v_mfma_f32_16x16x32_bf16 v[144:147], v[116:119], v[44:47], v[144:147]
	v_mfma_f32_16x16x32_bf16 v[104:107], v[116:119], v[48:51], v[104:107]
	v_mfma_f32_16x16x32_bf16 v[32:35], v[116:119], v[56:59], v[32:35]
	v_mfma_f32_16x16x32_bf16 v[0:3], v[116:119], v[60:63], v[0:3]
	s_waitcnt lgkmcnt(3)
	v_mfma_f32_16x16x32_bf16 v[172:175], v[176:179], v[44:47], v[172:175]
	v_mfma_f32_16x16x32_bf16 v[140:143], v[176:179], v[48:51], v[140:143]
	v_mfma_f32_16x16x32_bf16 v[96:99], v[176:179], v[56:59], v[96:99]
	v_mfma_f32_16x16x32_bf16 v[28:31], v[176:179], v[60:63], v[28:31]
	s_waitcnt lgkmcnt(2)
	v_mfma_f32_16x16x32_bf16 v[168:171], v[180:183], v[44:47], v[168:171]
	v_mfma_f32_16x16x32_bf16 v[136:139], v[180:183], v[48:51], v[136:139]
	v_mfma_f32_16x16x32_bf16 v[88:91], v[180:183], v[56:59], v[88:91]
	v_mfma_f32_16x16x32_bf16 v[24:27], v[180:183], v[60:63], v[24:27]
	s_waitcnt lgkmcnt(0)
	s_mov_b32 s13, 5

.LBB0_896:
	s_andn2_b64 vcc, exec, s[2:3]
	s_cbranch_vccnz .LBB0_890
	v_readlane_b32 s11, v254, 62
	v_readlane_b32 s12, v254, 60
	v_readlane_b32 s2, v253, 4
	v_readlane_b32 s3, v253, 5
	s_lshl_b32 s13, s11, 18
	s_add_u32 s2, s2, s13
	s_addc_u32 s3, s3, 0
	s_lshl_b32 s13, s12, 19
	s_add_u32 s4, s50, 0x65d0000
	s_addc_u32 s5, s51, 0
	s_add_u32 s4, s4, s13
	s_addc_u32 s5, s5, 0
	v_and_b32_e32 v152, 63, v216
	v_lshrrev_b32_e32 v153, 6, v216
	v_lshrrev_b32_e32 v154, 2, v152
	v_and_b32_e32 v155, 3, v152
	v_readfirstlane_b32 s11, v153
	v_lshrrev_b32_e32 v156, 3, v154
	v_mul_u32_u24_e32 v156, 3, v156
	v_xor_b32_e32 v156, v155, v156
	v_lshlrev_b32_e32 v156, 4, v156
	v_lshl_add_u32 v157, v153, 5, v154
	v_lshl_add_u32 v203, v157, 11, v156
	v_add_u32_e32 v204, 0x8000, v203
	v_lshl_add_u32 v157, v153, 6, v154
	v_lshl_add_u32 v205, v157, 11, v156
	v_add_u32_e32 v206, 0x8000, v205
	v_add_u32_e32 v207, 0x10000, v205
	v_add_u32_e32 v208, 0x18000, v205
	v_and_b32_e32 v158, 15, v152
	v_lshrrev_b32_e32 v159, 4, v152
	v_lshrrev_b32_e32 v160, 3, v158
	v_mul_u32_u24_e32 v160, 3, v160
	v_xor_b32_e32 v160, v159, v160
	v_lshlrev_b32_e32 v160, 4, v160
	v_lshl_add_u32 v160, v158, 6, v160
	v_lshrrev_b32_e32 v161, 1, v153
	v_and_b32_e32 v162, 1, v153
	v_lshl_add_u32 v209, v161, 12, v160
	v_lshl_add_u32 v210, v162, 13, v160
	s_lshl_b32 s12, s11, 12
	s_lshl_b32 s11, s11, 11
	s_barrier
	s_add_u32 m0, s11, 0x0
	s_nop 0
	global_load_lds_dwordx4 v203, s[2:3]
	s_add_u32 m0, s11, 0x400
	s_nop 0
	global_load_lds_dwordx4 v204, s[2:3]
	s_add_u32 m0, s12, 0x2000
	s_nop 0
	global_load_lds_dwordx4 v205, s[4:5]
	s_add_u32 m0, s12, 0x2400
	s_nop 0
	global_load_lds_dwordx4 v206, s[4:5]
	s_add_u32 m0, s12, 0x2800
	s_nop 0
	global_load_lds_dwordx4 v207, s[4:5]
	s_add_u32 m0, s12, 0x2c00
	s_nop 0
	global_load_lds_dwordx4 v208, s[4:5]
	s_add_u32 s2, s2, 0x40
	s_addc_u32 s3, s3, 0
	s_add_u32 s4, s4, 0x40
	s_addc_u32 s5, s5, 0
	s_add_u32 m0, s11, 0x6000
	s_nop 0
	global_load_lds_dwordx4 v203, s[2:3]
	s_add_u32 m0, s11, 0x6400
	s_nop 0
	global_load_lds_dwordx4 v204, s[2:3]
	s_add_u32 m0, s12, 0x8000
	s_nop 0
	global_load_lds_dwordx4 v205, s[4:5]
	s_add_u32 m0, s12, 0x8400
	s_nop 0
	global_load_lds_dwordx4 v206, s[4:5]
	s_add_u32 m0, s12, 0x8800
	s_nop 0
	global_load_lds_dwordx4 v207, s[4:5]
	s_add_u32 m0, s12, 0x8c00
	s_nop 0
	global_load_lds_dwordx4 v208, s[4:5]
	s_add_u32 s2, s2, 0x40
	s_addc_u32 s3, s3, 0
	s_add_u32 s4, s4, 0x40
	s_addc_u32 s5, s5, 0
	v_mov_b32_e32 v172, 0
	v_mov_b32_e32 v173, 0
	v_mov_b32_e32 v174, 0
	v_mov_b32_e32 v175, 0
	v_mov_b32_e32 v168, 0
	v_mov_b32_e32 v169, 0
	v_mov_b32_e32 v170, 0
	v_mov_b32_e32 v171, 0
	v_mov_b32_e32 v116, 0
	v_mov_b32_e32 v117, 0
	v_mov_b32_e32 v118, 0
	v_mov_b32_e32 v119, 0
	v_mov_b32_e32 v112, 0
	v_mov_b32_e32 v113, 0
	v_mov_b32_e32 v114, 0
	v_mov_b32_e32 v115, 0
	v_mov_b32_e32 v108, 0
	v_mov_b32_e32 v109, 0
	v_mov_b32_e32 v110, 0
	v_mov_b32_e32 v111, 0
	v_mov_b32_e32 v104, 0
	v_mov_b32_e32 v105, 0
	v_mov_b32_e32 v106, 0
	v_mov_b32_e32 v107, 0
	v_mov_b32_e32 v100, 0
	v_mov_b32_e32 v101, 0
	v_mov_b32_e32 v102, 0
	v_mov_b32_e32 v103, 0
	v_mov_b32_e32 v96, 0
	v_mov_b32_e32 v97, 0
	v_mov_b32_e32 v98, 0
	v_mov_b32_e32 v99, 0
	v_mov_b32_e32 v92, 0
	v_mov_b32_e32 v93, 0
	v_mov_b32_e32 v94, 0
	v_mov_b32_e32 v95, 0
	v_mov_b32_e32 v88, 0
	v_mov_b32_e32 v89, 0
	v_mov_b32_e32 v90, 0
	v_mov_b32_e32 v91, 0
	v_mov_b32_e32 v84, 0
	v_mov_b32_e32 v85, 0
	v_mov_b32_e32 v86, 0
	v_mov_b32_e32 v87, 0
	v_mov_b32_e32 v80, 0
	v_mov_b32_e32 v81, 0
	v_mov_b32_e32 v82, 0
	v_mov_b32_e32 v83, 0
	v_mov_b32_e32 v76, 0
	v_mov_b32_e32 v77, 0
	v_mov_b32_e32 v78, 0
	v_mov_b32_e32 v79, 0
	v_mov_b32_e32 v72, 0
	v_mov_b32_e32 v73, 0
	v_mov_b32_e32 v74, 0
	v_mov_b32_e32 v75, 0
	v_mov_b32_e32 v68, 0
	v_mov_b32_e32 v69, 0
	v_mov_b32_e32 v70, 0
	v_mov_b32_e32 v71, 0
	v_mov_b32_e32 v64, 0
	v_mov_b32_e32 v65, 0
	v_mov_b32_e32 v66, 0
	v_mov_b32_e32 v67, 0
	v_mov_b32_e32 v60, 0
	v_mov_b32_e32 v61, 0
	v_mov_b32_e32 v62, 0
	v_mov_b32_e32 v63, 0
	v_mov_b32_e32 v56, 0
	v_mov_b32_e32 v57, 0
	v_mov_b32_e32 v58, 0
	v_mov_b32_e32 v59, 0
	v_mov_b32_e32 v52, 0
	v_mov_b32_e32 v53, 0
	v_mov_b32_e32 v54, 0
	v_mov_b32_e32 v55, 0
	v_mov_b32_e32 v48, 0
	v_mov_b32_e32 v49, 0
	v_mov_b32_e32 v50, 0
	v_mov_b32_e32 v51, 0
	v_mov_b32_e32 v44, 0
	v_mov_b32_e32 v45, 0
	v_mov_b32_e32 v46, 0
	v_mov_b32_e32 v47, 0
	v_mov_b32_e32 v40, 0
	v_mov_b32_e32 v41, 0
	v_mov_b32_e32 v42, 0
	v_mov_b32_e32 v43, 0
	v_mov_b32_e32 v36, 0
	v_mov_b32_e32 v37, 0
	v_mov_b32_e32 v38, 0
	v_mov_b32_e32 v39, 0
	v_mov_b32_e32 v32, 0
	v_mov_b32_e32 v33, 0
	v_mov_b32_e32 v34, 0
	v_mov_b32_e32 v35, 0
	v_mov_b32_e32 v28, 0
	v_mov_b32_e32 v29, 0
	v_mov_b32_e32 v30, 0
	v_mov_b32_e32 v31, 0
	v_mov_b32_e32 v24, 0
	v_mov_b32_e32 v25, 0
	v_mov_b32_e32 v26, 0
	v_mov_b32_e32 v27, 0
	v_mov_b32_e32 v20, 0
	v_mov_b32_e32 v21, 0
	v_mov_b32_e32 v22, 0
	v_mov_b32_e32 v23, 0
	v_mov_b32_e32 v16, 0
	v_mov_b32_e32 v17, 0
	v_mov_b32_e32 v18, 0
	v_mov_b32_e32 v19, 0
	v_mov_b32_e32 v12, 0
	v_mov_b32_e32 v13, 0
	v_mov_b32_e32 v14, 0
	v_mov_b32_e32 v15, 0
	v_mov_b32_e32 v8, 0
	v_mov_b32_e32 v9, 0
	v_mov_b32_e32 v10, 0
	v_mov_b32_e32 v11, 0
	v_mov_b32_e32 v4, 0
	v_mov_b32_e32 v5, 0
	v_mov_b32_e32 v6, 0
	v_mov_b32_e32 v7, 0
	v_mov_b32_e32 v0, 0
	v_mov_b32_e32 v1, 0
	v_mov_b32_e32 v2, 0
	v_mov_b32_e32 v3, 0
	s_waitcnt vmcnt(6)
	s_barrier
	ds_read_b128 v[120:123], v209 offset:0
	ds_read_b128 v[124:127], v209 offset:1024
	ds_read_b128 v[128:131], v209 offset:2048
	ds_read_b128 v[132:135], v209 offset:3072
	ds_read_b128 v[152:155], v210 offset:8192
	ds_read_b128 v[156:159], v210 offset:9216
	ds_read_b128 v[160:163], v210 offset:10240
	ds_read_b128 v[164:167], v210 offset:11264
	ds_read_b128 v[176:179], v210 offset:12288
	ds_read_b128 v[180:183], v210 offset:13312
	s_add_u32 m0, s11, 0xc000
	s_nop 0
	global_load_lds_dwordx4 v203, s[2:3]
	s_add_u32 m0, s11, 0xc400
	s_nop 0
	global_load_lds_dwordx4 v204, s[2:3]
	s_add_u32 m0, s12, 0xe000
	s_nop 0
	global_load_lds_dwordx4 v205, s[4:5]
	s_add_u32 m0, s12, 0xe400
	s_nop 0
	global_load_lds_dwordx4 v206, s[4:5]
	s_add_u32 m0, s12, 0xe800
	s_nop 0
	global_load_lds_dwordx4 v207, s[4:5]
	s_add_u32 m0, s12, 0xec00
	s_nop 0
	global_load_lds_dwordx4 v208, s[4:5]
	s_add_u32 s2, s2, 0x40
	s_addc_u32 s3, s3, 0
	s_add_u32 s4, s4, 0x40
	s_addc_u32 s5, s5, 0
	ds_read_b128 v[184:187], v210 offset:14336
	ds_read_b128 v[188:191], v210 offset:15360
	s_waitcnt lgkmcnt(7)
	v_mfma_f32_16x16x32_bf16 v[172:175], v[152:155], v[120:123], v[172:175]
	v_mfma_f32_16x16x32_bf16 v[92:95], v[152:155], v[124:127], v[92:95]
	v_mfma_f32_16x16x32_bf16 v[60:63], v[152:155], v[128:131], v[60:63]
	v_mfma_f32_16x16x32_bf16 v[28:31], v[152:155], v[132:135], v[28:31]
	s_waitcnt lgkmcnt(6)
	v_mfma_f32_16x16x32_bf16 v[168:171], v[156:159], v[120:123], v[168:171]
	v_mfma_f32_16x16x32_bf16 v[88:91], v[156:159], v[124:127], v[88:91]
	v_mfma_f32_16x16x32_bf16 v[56:59], v[156:159], v[128:131], v[56:59]
	v_mfma_f32_16x16x32_bf16 v[24:27], v[156:159], v[132:135], v[24:27]
	s_waitcnt lgkmcnt(5)
	v_mfma_f32_16x16x32_bf16 v[116:119], v[160:163], v[120:123], v[116:119]
	v_mfma_f32_16x16x32_bf16 v[84:87], v[160:163], v[124:127], v[84:87]
	v_mfma_f32_16x16x32_bf16 v[52:55], v[160:163], v[128:131], v[52:55]
	v_mfma_f32_16x16x32_bf16 v[20:23], v[160:163], v[132:135], v[20:23]
	s_waitcnt lgkmcnt(4)
	v_mfma_f32_16x16x32_bf16 v[112:115], v[164:167], v[120:123], v[112:115]
	v_mfma_f32_16x16x32_bf16 v[80:83], v[164:167], v[124:127], v[80:83]
	v_mfma_f32_16x16x32_bf16 v[48:51], v[164:167], v[128:131], v[48:51]
	v_mfma_f32_16x16x32_bf16 v[16:19], v[164:167], v[132:135], v[16:19]
	s_waitcnt lgkmcnt(3)
	v_mfma_f32_16x16x32_bf16 v[108:111], v[176:179], v[120:123], v[108:111]
	v_mfma_f32_16x16x32_bf16 v[76:79], v[176:179], v[124:127], v[76:79]
	v_mfma_f32_16x16x32_bf16 v[44:47], v[176:179], v[128:131], v[44:47]
	v_mfma_f32_16x16x32_bf16 v[12:15], v[176:179], v[132:135], v[12:15]
	s_waitcnt lgkmcnt(2)
	v_mfma_f32_16x16x32_bf16 v[104:107], v[180:183], v[120:123], v[104:107]
	v_mfma_f32_16x16x32_bf16 v[72:75], v[180:183], v[124:127], v[72:75]
	v_mfma_f32_16x16x32_bf16 v[40:43], v[180:183], v[128:131], v[40:43]
	v_mfma_f32_16x16x32_bf16 v[8:11], v[180:183], v[132:135], v[8:11]
	s_waitcnt lgkmcnt(0)
	s_mov_b32 s13, 5
